# v53 + GEMM: the dummy cross-tile prefetch of a workgroup's last tile points at K-tiles the loop has just loaded instead of the tile's first K-tiles
# speedup vs baseline: 1.0089x; 1.0030x over previous
; template <class Epi, class Sched, bool ALIGN_EPI = false, bool SP2 = false>
; __device__ __forceinline__ void gemm_phase(PG8_LAS unsigned char* lds, const Gemm g, const Sched& S, const Epi& E) {
;     ...
;         const bool has_next = S.next(ui + 1, nxt);
;         const char* nA = has_next ? (const char*)g.A + (size_t)nxt.pm * tstep : cA; const char* nB = has_next ? (const char*)g.Bt + (size_t)nxt.pn * tstep : cB;
.LBB0_222:
	s_nop 0
	v_cndmask_b32_e64 v2, 0, 1, s[42:43]
	v_cmp_ne_u32_e64 s[40:41], 1, v2
	s_andn2_b64 vcc, exec, s[42:43]
	s_add_i32 s2, s91, -2
	s_lshl_b32 s2, s2, 7
	s_add_u32 s42, s16, s2
	s_addc_u32 s43, s17, 0
	s_cbranch_vccnz .LBB0_224
	s_ashr_i32 s2, s8, 31
	s_mul_hi_u32 s4, s52, s8
	s_mul_i32 s2, s52, s2
	s_add_i32 s2, s4, s2
	s_mul_i32 s4, s53, s8
	s_add_i32 s2, s2, s4
	s_mul_i32 s4, s52, s8
	s_add_u32 s42, s46, s4
	s_addc_u32 s43, s47, s2
.LBB0_224:
	s_and_b64 vcc, exec, s[40:41]
	s_add_i32 s2, s91, -2
	s_lshl_b32 s2, s2, 7
	s_add_u32 s62, s12, s2
	s_addc_u32 s63, s13, 0
	s_cbranch_vccnz .LBB0_226
	s_ashr_i32 s2, s51, 31
	s_mul_hi_u32 s4, s52, s51
	s_mul_i32 s2, s52, s2
	s_add_i32 s2, s4, s2
	s_mul_i32 s4, s53, s51
	s_add_i32 s2, s2, s4
	s_mul_i32 s4, s52, s51
	s_add_u32 s62, s44, s4
	s_addc_u32 s63, s45, s2
